# pooling phase: a wave's pooling group (window 2/4/8/16) advances every loop iteration instead of being fixed by the wave index, so all waves carry the same load mix
# speedup vs baseline: 1.1223x; 1.0082x over previous
.LBB0_2095:
	s_or_b64 exec, exec, s[8:9]
	v_add_u32_e32 v66, s66, v66
	s_mov_b32 s2, 0xffff
	v_cvt_pk_bf16_f32 v3, v2, v3
	v_cvt_pk_bf16_f32 v2, v0, v1
	v_lshlrev_b64 v[0:1], 11, v[64:65]
	v_cmp_lt_i32_e32 vcc, s2, v66
	v_cvt_pk_bf16_f32 v4, v4, v5
	v_cvt_pk_bf16_f32 v5, v6, v7
	v_lshl_add_u64 v[0:1], v[62:63], 0, v[0:1]
	s_or_b64 s[92:93], vcc, s[92:93]
	global_store_dwordx4 v[0:1], v[2:5], off
	v_add_u32_e32 v68, 1, v68
	v_and_b32_e32 v68, 3, v68
	v_cmp_eq_u32_e32 vcc, 0, v68
	v_cndmask_b32_e64 v94, 0, 1, vcc
	v_lshlrev_b32_e32 v94, 11, v94
	v_sub_u32_e32 v94, 0x200, v94
	v_ashrrev_i32_e32 v95, 31, v94
	v_lshl_add_u64 v[60:61], v[60:61], 0, v[94:95]
	v_lshl_add_u64 v[62:63], v[62:63], 0, v[94:95]
	s_andn2_b64 exec, exec, s[92:93]
	s_cbranch_execz .LBB0_2108
